# GEMM K-loop: next-tile bookkeeping moved behind the phase-0 LDS reads, vmcnt and lgkmcnt waits merged, remaining priority flips removed
# baseline (speedup 1.0000x reference)
; #define PG8_STAGE(bufoff, gbase, voff) do { _Pragma("unroll") for (int _i = 0; _i < 2; ++_i) \
;         __builtin_amdgcn_global_load_lds((const unsigned*)((const char*)(gbase) + (voff)[_i]), (LAS unsigned*)(lds + (bufoff) + ldsw + _i * 8192), 16, 0, 0); } while (0)
; #define PG8_LDA(dst, b, h) do { _Pragma("unroll") for (int m = 0; m < 4; ++m) _Pragma("unroll") for (int k = 0; k < 2; ++k) dst[m][k] = *(const LAS bf16x8*)(lds + PG8_SA(b, h) + aoff + m * 2048 + k * 1024); } while (0)
; #define PG8_LDB(dst, b, h) do { _Pragma("unroll") for (int n = 0; n < 2; ++n) _Pragma("unroll") for (int k = 0; k < 2; ++k) dst[n][k] = *(const LAS bf16x8*)(lds + PG8_SB(b, h) + boff + n * 2048 + k * 1024); } while (0)
; #define PG8_MMA(ai, bj, At, Bt) do { __builtin_amdgcn_s_setprio(1); _Pragma("unroll") for (int m = 0; m < 4; ++m) _Pragma("unroll") for (int n = 0; n < 2; ++n) _Pragma("unroll") for (int k = 0; k < 2; ++k) \
;         acc[ai][bj][m][n] = __builtin_amdgcn_mfma_f32_16x16x32_bf16(Bt[n][k], At[m][k], acc[ai][bj][m][n], 0, 0, 0); __builtin_amdgcn_s_setprio(0); } while (0)
; #define PG8_WAIT_V(n) asm volatile("s_waitcnt vmcnt(" #n ")" ::: "memory")
; #define PG8_WAIT_L(n) asm volatile("s_waitcnt lgkmcnt(" #n ")" ::: "memory")
; #define PG8_BAR __builtin_amdgcn_s_barrier()
; #define PG8_SCHED __builtin_amdgcn_sched_barrier(0)
; template <class Epi>
; DI void gemm_phase(LAS unsigned char* lds, const Gemm g, const StaticOrder& S, const Epi& E) {
;     ...
;         for (int t = 0; t < nt; t += 2) {
;             const bool last = (t == nt - 2);
;             const char* a1 = cA + (size_t)(t + 1) * kstep;
;             const char* a2 = last ? nA : cA + (size_t)(t + 2) * kstep; const char* b2 = last ? nB : cB + (size_t)(t + 2) * kstep;
;             const char* a3 = a2 + kstep; const char* b3 = b2 + kstep;
;             PG8_LDB(B0, 0, 0); PG8_LDB(B1, 0, 1); PG8_SCHED; PG8_LDA(At, 0, 0); PG8_STAGE(PG8_SA(1, 1), a1 + hstepA, voffA);
;             PG8_WAIT_V(8); PG8_WAIT_L(0); PG8_BAR; PG8_MMA(0, 0, At, B0); PG8_MMA(0, 1, At, B1); PG8_BAR; PG8_SCHED;
;     ...
; #pragma unroll
;         for (int a = 0; a < 2; ++a)
; #pragma unroll
;             for (int b = 0; b < 2; ++b)
; #pragma unroll
;                 for (int m = 0; m < 4; ++m)
; #pragma unroll
;                     for (int n = 0; n < 2; ++n) acc[a][b][m][n] = (f32x4){0.f, 0.f, 0.f, 0.f};
;         cur = nxt; cA = nA; cB = nB; ++ui;
.LBB0_445:
	s_add_u32 s16, s36, 0x100
	s_addc_u32 s29, s37, 0
	s_add_u32 s0, s48, 0x80
	v_mov_b32_e32 v2, 0
	s_addc_u32 s1, s49, 0
	s_mov_b32 s33, 0
	v_mov_b32_e32 v3, v2
	v_mov_b32_e32 v4, v2
	v_mov_b32_e32 v5, v2
	v_mov_b32_e32 v6, v2
	v_mov_b32_e32 v7, v2
	v_mov_b32_e32 v8, v2
	v_mov_b32_e32 v9, v2
	v_mov_b32_e32 v18, v2
	v_mov_b32_e32 v19, v2
	v_mov_b32_e32 v20, v2
	v_mov_b32_e32 v21, v2
	v_mov_b32_e32 v22, v2
	v_mov_b32_e32 v23, v2
	v_mov_b32_e32 v24, v2
	v_mov_b32_e32 v25, v2
	v_mov_b32_e32 v34, v2
	v_mov_b32_e32 v35, v2
	v_mov_b32_e32 v36, v2
	v_mov_b32_e32 v37, v2
	v_mov_b32_e32 v38, v2
	v_mov_b32_e32 v39, v2
	v_mov_b32_e32 v40, v2
	v_mov_b32_e32 v41, v2
	v_mov_b32_e32 v50, v2
	v_mov_b32_e32 v51, v2
	v_mov_b32_e32 v52, v2
	v_mov_b32_e32 v53, v2
	v_mov_b32_e32 v54, v2
	v_mov_b32_e32 v55, v2
	v_mov_b32_e32 v56, v2
	v_mov_b32_e32 v57, v2
	v_mov_b32_e32 v10, v2
	v_mov_b32_e32 v11, v2
	v_mov_b32_e32 v12, v2
	v_mov_b32_e32 v13, v2
	v_mov_b32_e32 v14, v2
	v_mov_b32_e32 v15, v2
	v_mov_b32_e32 v16, v2
	v_mov_b32_e32 v17, v2
	v_mov_b32_e32 v26, v2
	v_mov_b32_e32 v27, v2
	v_mov_b32_e32 v28, v2
	v_mov_b32_e32 v29, v2
	v_mov_b32_e32 v30, v2
	v_mov_b32_e32 v31, v2
	v_mov_b32_e32 v32, v2
	v_mov_b32_e32 v33, v2
	v_mov_b32_e32 v42, v2
	v_mov_b32_e32 v43, v2
	v_mov_b32_e32 v44, v2
	v_mov_b32_e32 v45, v2
	v_mov_b32_e32 v46, v2
	v_mov_b32_e32 v47, v2
	v_mov_b32_e32 v48, v2
	v_mov_b32_e32 v49, v2
	v_mov_b32_e32 v58, v2
	v_mov_b32_e32 v59, v2
	v_mov_b32_e32 v60, v2
	v_mov_b32_e32 v61, v2
	v_mov_b32_e32 v62, v2
	v_mov_b32_e32 v63, v2
	v_mov_b32_e32 v64, v2
	v_mov_b32_e32 v65, v2
	v_mov_b32_e32 v66, v2
	v_mov_b32_e32 v67, v2
	v_mov_b32_e32 v68, v2
	v_mov_b32_e32 v69, v2
	v_mov_b32_e32 v70, v2
	v_mov_b32_e32 v71, v2
	v_mov_b32_e32 v72, v2
	v_mov_b32_e32 v73, v2
	v_mov_b32_e32 v82, v2
	v_mov_b32_e32 v83, v2
	v_mov_b32_e32 v84, v2
	v_mov_b32_e32 v85, v2
	v_mov_b32_e32 v86, v2
	v_mov_b32_e32 v87, v2
	v_mov_b32_e32 v88, v2
	v_mov_b32_e32 v89, v2
	v_mov_b32_e32 v98, v2
	v_mov_b32_e32 v99, v2
	v_mov_b32_e32 v100, v2
	v_mov_b32_e32 v101, v2
	v_mov_b32_e32 v102, v2
	v_mov_b32_e32 v103, v2
	v_mov_b32_e32 v104, v2
	v_mov_b32_e32 v105, v2
	v_mov_b32_e32 v114, v2
	v_mov_b32_e32 v115, v2
	v_mov_b32_e32 v116, v2
	v_mov_b32_e32 v117, v2
	v_mov_b32_e32 v118, v2
	v_mov_b32_e32 v119, v2
	v_mov_b32_e32 v120, v2
	v_mov_b32_e32 v121, v2
	v_mov_b32_e32 v74, v2
	v_mov_b32_e32 v75, v2
	v_mov_b32_e32 v76, v2
	v_mov_b32_e32 v77, v2
	v_mov_b32_e32 v78, v2
	v_mov_b32_e32 v79, v2
	v_mov_b32_e32 v80, v2
	v_mov_b32_e32 v81, v2
	v_mov_b32_e32 v90, v2
	v_mov_b32_e32 v91, v2
	v_mov_b32_e32 v92, v2
	v_mov_b32_e32 v93, v2
	v_mov_b32_e32 v94, v2
	v_mov_b32_e32 v95, v2
	v_mov_b32_e32 v96, v2
	v_mov_b32_e32 v97, v2
	v_mov_b32_e32 v106, v2
	v_mov_b32_e32 v107, v2
	v_mov_b32_e32 v108, v2
	v_mov_b32_e32 v109, v2
	v_mov_b32_e32 v110, v2
	v_mov_b32_e32 v111, v2
	v_mov_b32_e32 v112, v2
	v_mov_b32_e32 v113, v2
	v_mov_b32_e32 v122, v2
	v_mov_b32_e32 v123, v2
	v_mov_b32_e32 v124, v2
	v_mov_b32_e32 v125, v2
	v_mov_b32_e32 v126, v2
	v_mov_b32_e32 v127, v2
	v_mov_b32_e32 v128, v2
	v_mov_b32_e32 v129, v2
	s_waitcnt vmcnt(0) lgkmcnt(0)
.LBB0_446:
	s_add_i32 s50, 0, 0x10000
	v_add_u32_e32 v0, s50, v238
	ds_read_b128 v[130:133], v0
	ds_read_b128 v[134:137], v0 offset:1024
	ds_read_b128 v[138:141], v0 offset:2048
	ds_read_b128 v[142:145], v0 offset:3072
	v_add_u32_e32 v0, 0x14000, v238
	ds_read_b128 v[146:149], v0
	ds_read_b128 v[150:153], v0 offset:1024
	ds_read_b128 v[154:157], v0 offset:2048
	ds_read_b128 v[158:161], v0 offset:3072
	v_lshl_add_u64 v[194:195], s[0:1], 0, v[214:215]
	s_add_i32 m0, s13, 0xc000
	ds_read_b128 v[162:165], v245
	ds_read_b128 v[166:169], v245 offset:1024
	ds_read_b128 v[170:173], v245 offset:2048
	ds_read_b128 v[174:177], v245 offset:3072
	ds_read_b128 v[178:181], v245 offset:4096
	ds_read_b128 v[182:185], v245 offset:5120
	ds_read_b128 v[186:189], v245 offset:6144
	ds_read_b128 v[190:193], v245 offset:7168
	global_load_lds_dwordx4 v[194:195], off
	s_add_i32 m0, s13, 0xe000
	v_lshl_add_u64 v[194:195], s[0:1], 0, v[212:213]
	global_load_lds_dwordx4 v[194:195], off
	s_add_i32 s2, s33, 2
	s_add_u32 s3, s0, 0x80
	s_addc_u32 s36, s1, 0
	s_cmp_eq_u32 s18, s33
	s_cselect_b32 s37, s31, s36
	s_cselect_b32 s36, s30, s3
	s_cselect_b32 s49, s27, s29
	s_cselect_b32 s48, s26, s16
	s_add_i32 s3, 0, 0x14000
	s_waitcnt vmcnt(8) lgkmcnt(0)
	s_barrier
	v_mfma_f32_16x16x32_bf16 v[126:129], v[130:133], v[162:165], v[126:129]
	v_mfma_f32_16x16x32_bf16 v[122:125], v[138:141], v[162:165], v[122:125]
	v_mfma_f32_16x16x32_bf16 v[110:113], v[130:133], v[170:173], v[110:113]
	v_mfma_f32_16x16x32_bf16 v[106:109], v[138:141], v[170:173], v[106:109]
	v_mfma_f32_16x16x32_bf16 v[94:97], v[130:133], v[178:181], v[94:97]
	v_mfma_f32_16x16x32_bf16 v[90:93], v[138:141], v[178:181], v[90:93]
	v_mfma_f32_16x16x32_bf16 v[78:81], v[130:133], v[186:189], v[78:81]
	v_mfma_f32_16x16x32_bf16 v[74:77], v[138:141], v[186:189], v[74:77]
	v_mfma_f32_16x16x32_bf16 v[126:129], v[134:137], v[166:169], v[126:129]
	v_mfma_f32_16x16x32_bf16 v[122:125], v[142:145], v[166:169], v[122:125]
	v_mfma_f32_16x16x32_bf16 v[110:113], v[134:137], v[174:177], v[110:113]
	v_mfma_f32_16x16x32_bf16 v[106:109], v[142:145], v[174:177], v[106:109]
	v_mfma_f32_16x16x32_bf16 v[94:97], v[134:137], v[182:185], v[94:97]
	v_mfma_f32_16x16x32_bf16 v[90:93], v[142:145], v[182:185], v[90:93]
	v_mfma_f32_16x16x32_bf16 v[78:81], v[134:137], v[190:193], v[78:81]
	v_mfma_f32_16x16x32_bf16 v[74:77], v[142:145], v[190:193], v[74:77]
	v_mfma_f32_16x16x32_bf16 v[118:121], v[146:149], v[162:165], v[118:121]
	v_mfma_f32_16x16x32_bf16 v[114:117], v[154:157], v[162:165], v[114:117]
	v_mfma_f32_16x16x32_bf16 v[102:105], v[146:149], v[170:173], v[102:105]
	v_mfma_f32_16x16x32_bf16 v[98:101], v[154:157], v[170:173], v[98:101]
	v_mfma_f32_16x16x32_bf16 v[86:89], v[146:149], v[178:181], v[86:89]
	v_mfma_f32_16x16x32_bf16 v[82:85], v[154:157], v[178:181], v[82:85]
	v_mfma_f32_16x16x32_bf16 v[70:73], v[146:149], v[186:189], v[70:73]
	v_mfma_f32_16x16x32_bf16 v[66:69], v[154:157], v[186:189], v[66:69]
	v_mfma_f32_16x16x32_bf16 v[118:121], v[150:153], v[166:169], v[118:121]
	v_mfma_f32_16x16x32_bf16 v[114:117], v[158:161], v[166:169], v[114:117]
	v_mfma_f32_16x16x32_bf16 v[102:105], v[150:153], v[174:177], v[102:105]
	v_mfma_f32_16x16x32_bf16 v[98:101], v[158:161], v[174:177], v[98:101]
	v_mfma_f32_16x16x32_bf16 v[86:89], v[150:153], v[182:185], v[86:89]
	v_mfma_f32_16x16x32_bf16 v[82:85], v[158:161], v[182:185], v[82:85]
	v_mfma_f32_16x16x32_bf16 v[70:73], v[150:153], v[190:193], v[70:73]
	v_mfma_f32_16x16x32_bf16 v[66:69], v[158:161], v[190:193], v[66:69]
	s_barrier
; #define PG8_STAGE(bufoff, gbase, voff) do { _Pragma("unroll") for (int _i = 0; _i < 2; ++_i) \
;         __builtin_amdgcn_global_load_lds((const unsigned*)((const char*)(gbase) + (voff)[_i]), (LAS unsigned*)(lds + (bufoff) + ldsw + _i * 8192), 16, 0, 0); } while (0)
; #define PG8_LDA(dst, b, h) do { _Pragma("unroll") for (int m = 0; m < 4; ++m) _Pragma("unroll") for (int k = 0; k < 2; ++k) dst[m][k] = *(const LAS bf16x8*)(lds + PG8_SA(b, h) + aoff + m * 2048 + k * 1024); } while (0)
; #define PG8_LDB(dst, b, h) do { _Pragma("unroll") for (int n = 0; n < 2; ++n) _Pragma("unroll") for (int k = 0; k < 2; ++k) dst[n][k] = *(const LAS bf16x8*)(lds + PG8_SB(b, h) + boff + n * 2048 + k * 1024); } while (0)
; #define PG8_MMA(ai, bj, At, Bt) do { __builtin_amdgcn_s_setprio(1); _Pragma("unroll") for (int m = 0; m < 4; ++m) _Pragma("unroll") for (int n = 0; n < 2; ++n) _Pragma("unroll") for (int k = 0; k < 2; ++k) \
;         acc[ai][bj][m][n] = __builtin_amdgcn_mfma_f32_16x16x32_bf16(Bt[n][k], At[m][k], acc[ai][bj][m][n], 0, 0, 0); __builtin_amdgcn_s_setprio(0); } while (0)
; #define PG8_WAIT_V(n) asm volatile("s_waitcnt vmcnt(" #n ")" ::: "memory")
; #define PG8_WAIT_L(n) asm volatile("s_waitcnt lgkmcnt(" #n ")" ::: "memory")
; #define PG8_BAR __builtin_amdgcn_s_barrier()
; #define PG8_SCHED __builtin_amdgcn_sched_barrier(0)
; template <class Epi>
; DI void gemm_phase(LAS unsigned char* lds, const Gemm g, const StaticOrder& S, const Epi& E) {
;     ...
;             PG8_LDA(At, 0, 1); PG8_STAGE(PG8_SB(0, 0), b2, voffB); PG8_STAGE(PG8_SB(0, 1), b2 + hstepB, voffB); PG8_STAGE(PG8_SA(0, 0), a2, voffA);
;             PG8_WAIT_V(8); PG8_WAIT_L(0); PG8_BAR; PG8_MMA(1, 0, At, B0); PG8_MMA(1, 1, At, B1); PG8_BAR; PG8_SCHED;
;             PG8_LDB(B0, 1, 0); PG8_LDB(B1, 1, 1); PG8_SCHED; PG8_LDA(At, 1, 0); PG8_STAGE(PG8_SA(0, 1), a2 + hstepA, voffA);
;             PG8_WAIT_V(8); PG8_WAIT_L(0); PG8_BAR; PG8_MMA(0, 0, At, B0); PG8_MMA(0, 1, At, B1); PG8_BAR; PG8_SCHED;
	s_add_i32 s33, s50, s12
	v_lshl_add_u64 v[194:195], s[48:49], 0, v[200:201]
	s_mov_b32 m0, s33
	ds_read_b128 v[162:165], v245 offset:16384
	ds_read_b128 v[166:169], v245 offset:17408
	ds_read_b128 v[170:173], v245 offset:18432
	ds_read_b128 v[174:177], v245 offset:19456
	ds_read_b128 v[178:181], v245 offset:20480
	ds_read_b128 v[182:185], v245 offset:21504
	ds_read_b128 v[186:189], v245 offset:22528
	ds_read_b128 v[190:193], v245 offset:23552
	global_load_lds_dwordx4 v[194:195], off
	s_add_i32 m0, s33, 0x2000
	v_lshl_add_u64 v[196:197], s[48:49], 0, v[204:205]
	s_add_u32 s48, s48, s9
	s_addc_u32 s49, s49, 0
	s_add_i32 s3, s3, s12
	global_load_lds_dwordx4 v[196:197], off
	v_lshl_add_u64 v[216:217], s[48:49], 0, v[200:201]
	s_mov_b32 m0, s3
	v_lshl_add_u64 v[218:219], s[48:49], 0, v[204:205]
	global_load_lds_dwordx4 v[216:217], off
	s_add_i32 m0, s3, 0x2000
	v_lshl_add_u64 v[220:221], s[36:37], 0, v[198:199]
	global_load_lds_dwordx4 v[218:219], off
	s_mov_b32 m0, s13
	v_lshl_add_u64 v[222:223], s[36:37], 0, v[202:203]
	global_load_lds_dwordx4 v[220:221], off
	s_mov_b32 m0, s72
	s_nop 0
	global_load_lds_dwordx4 v[222:223], off
	s_waitcnt vmcnt(8) lgkmcnt(0)
	s_barrier
	v_mfma_f32_16x16x32_bf16 v[62:65], v[130:133], v[162:165], v[62:65]
	v_mfma_f32_16x16x32_bf16 v[58:61], v[138:141], v[162:165], v[58:61]
	v_mfma_f32_16x16x32_bf16 v[46:49], v[130:133], v[170:173], v[46:49]
	v_mfma_f32_16x16x32_bf16 v[42:45], v[138:141], v[170:173], v[42:45]
	v_mfma_f32_16x16x32_bf16 v[30:33], v[130:133], v[178:181], v[30:33]
	v_mfma_f32_16x16x32_bf16 v[26:29], v[138:141], v[178:181], v[26:29]
	v_mfma_f32_16x16x32_bf16 v[14:17], v[130:133], v[186:189], v[14:17]
	v_mfma_f32_16x16x32_bf16 v[10:13], v[138:141], v[186:189], v[10:13]
	v_mfma_f32_16x16x32_bf16 v[62:65], v[134:137], v[166:169], v[62:65]
	v_mfma_f32_16x16x32_bf16 v[58:61], v[142:145], v[166:169], v[58:61]
	v_mfma_f32_16x16x32_bf16 v[46:49], v[134:137], v[174:177], v[46:49]
	v_mfma_f32_16x16x32_bf16 v[42:45], v[142:145], v[174:177], v[42:45]
	v_mfma_f32_16x16x32_bf16 v[30:33], v[134:137], v[182:185], v[30:33]
	v_mfma_f32_16x16x32_bf16 v[26:29], v[142:145], v[182:185], v[26:29]
	v_mfma_f32_16x16x32_bf16 v[14:17], v[134:137], v[190:193], v[14:17]
	v_mfma_f32_16x16x32_bf16 v[10:13], v[142:145], v[190:193], v[10:13]
	v_mfma_f32_16x16x32_bf16 v[54:57], v[146:149], v[162:165], v[54:57]
	v_mfma_f32_16x16x32_bf16 v[50:53], v[154:157], v[162:165], v[50:53]
	v_mfma_f32_16x16x32_bf16 v[38:41], v[146:149], v[170:173], v[38:41]
	v_mfma_f32_16x16x32_bf16 v[34:37], v[154:157], v[170:173], v[34:37]
	v_mfma_f32_16x16x32_bf16 v[22:25], v[146:149], v[178:181], v[22:25]
	v_mfma_f32_16x16x32_bf16 v[18:21], v[154:157], v[178:181], v[18:21]
	v_mfma_f32_16x16x32_bf16 v[6:9], v[146:149], v[186:189], v[6:9]
	v_mfma_f32_16x16x32_bf16 v[2:5], v[154:157], v[186:189], v[2:5]
	v_mfma_f32_16x16x32_bf16 v[54:57], v[150:153], v[166:169], v[54:57]
	v_mfma_f32_16x16x32_bf16 v[50:53], v[158:161], v[166:169], v[50:53]
	v_mfma_f32_16x16x32_bf16 v[38:41], v[150:153], v[174:177], v[38:41]
	v_mfma_f32_16x16x32_bf16 v[34:37], v[158:161], v[174:177], v[34:37]
	v_mfma_f32_16x16x32_bf16 v[22:25], v[150:153], v[182:185], v[22:25]
	v_mfma_f32_16x16x32_bf16 v[18:21], v[158:161], v[182:185], v[18:21]
	v_mfma_f32_16x16x32_bf16 v[6:9], v[150:153], v[190:193], v[6:9]
	v_mfma_f32_16x16x32_bf16 v[2:5], v[158:161], v[190:193], v[2:5]
	s_barrier
	s_add_i32 s3, 0, 0x18000
	v_add_u32_e32 v0, s3, v238
	s_add_i32 s33, 0, 0x1c000
	ds_read_b128 v[130:133], v0
	ds_read_b128 v[134:137], v0 offset:1024
	ds_read_b128 v[138:141], v0 offset:2048
	ds_read_b128 v[142:145], v0 offset:3072
	v_add_u32_e32 v0, s33, v238
	ds_read_b128 v[146:149], v0
	ds_read_b128 v[150:153], v0 offset:1024
	ds_read_b128 v[154:157], v0 offset:2048
	ds_read_b128 v[158:161], v0 offset:3072
	s_add_u32 s36, s36, s56
	s_addc_u32 s37, s37, 0
	s_mov_b32 m0, s73
	v_lshl_add_u64 v[224:225], s[36:37], 0, v[198:199]
	ds_read_b128 v[162:165], v245 offset:32768
	ds_read_b128 v[166:169], v245 offset:33792
	ds_read_b128 v[170:173], v245 offset:34816
	ds_read_b128 v[174:177], v245 offset:35840
	ds_read_b128 v[178:181], v245 offset:36864
	ds_read_b128 v[182:185], v245 offset:37888
	ds_read_b128 v[186:189], v245 offset:38912
	ds_read_b128 v[190:193], v245 offset:39936
	global_load_lds_dwordx4 v[224:225], off
	s_mov_b32 m0, s74
	v_lshl_add_u64 v[224:225], s[36:37], 0, v[202:203]
	global_load_lds_dwordx4 v[224:225], off
	s_waitcnt vmcnt(8) lgkmcnt(0)
	s_barrier
; #define PG8_STAGE(bufoff, gbase, voff) do { _Pragma("unroll") for (int _i = 0; _i < 2; ++_i) \
;         __builtin_amdgcn_global_load_lds((const unsigned*)((const char*)(gbase) + (voff)[_i]), (LAS unsigned*)(lds + (bufoff) + ldsw + _i * 8192), 16, 0, 0); } while (0)
; #define PG8_LDA(dst, b, h) do { _Pragma("unroll") for (int m = 0; m < 4; ++m) _Pragma("unroll") for (int k = 0; k < 2; ++k) dst[m][k] = *(const LAS bf16x8*)(lds + PG8_SA(b, h) + aoff + m * 2048 + k * 1024); } while (0)
; #define PG8_MMA(ai, bj, At, Bt) do { __builtin_amdgcn_s_setprio(1); _Pragma("unroll") for (int m = 0; m < 4; ++m) _Pragma("unroll") for (int n = 0; n < 2; ++n) _Pragma("unroll") for (int k = 0; k < 2; ++k) \
;         acc[ai][bj][m][n] = __builtin_amdgcn_mfma_f32_16x16x32_bf16(Bt[n][k], At[m][k], acc[ai][bj][m][n], 0, 0, 0); __builtin_amdgcn_s_setprio(0); } while (0)
; #define PG8_WAIT_V(n) asm volatile("s_waitcnt vmcnt(" #n ")" ::: "memory")
; #define PG8_WAIT_L(n) asm volatile("s_waitcnt lgkmcnt(" #n ")" ::: "memory")
; #define PG8_BAR __builtin_amdgcn_s_barrier()
; #define PG8_SCHED __builtin_amdgcn_sched_barrier(0)
; template <class Epi>
; DI void gemm_phase(LAS unsigned char* lds, const Gemm g, const StaticOrder& S, const Epi& E) {
;     ...
;             PG8_WAIT_V(8); PG8_WAIT_L(0); PG8_BAR; PG8_MMA(0, 0, At, B0); PG8_MMA(0, 1, At, B1); PG8_BAR; PG8_SCHED;
;             PG8_LDA(At, 1, 1); PG8_STAGE(PG8_SB(1, 0), b3, voffB); PG8_STAGE(PG8_SB(1, 1), b3 + hstepB, voffB); PG8_STAGE(PG8_SA(1, 0), a3, voffA);
;             PG8_WAIT_V(8); PG8_WAIT_L(0); PG8_BAR; PG8_MMA(1, 0, At, B0); PG8_MMA(1, 1, At, B1); PG8_BAR; PG8_SCHED;
;         }
;         if (wr == 0) PG8_BAR;
	v_mfma_f32_16x16x32_bf16 v[126:129], v[130:133], v[162:165], v[126:129]
	v_mfma_f32_16x16x32_bf16 v[122:125], v[138:141], v[162:165], v[122:125]
	v_mfma_f32_16x16x32_bf16 v[110:113], v[130:133], v[170:173], v[110:113]
	v_mfma_f32_16x16x32_bf16 v[106:109], v[138:141], v[170:173], v[106:109]
	v_mfma_f32_16x16x32_bf16 v[94:97], v[130:133], v[178:181], v[94:97]
	v_mfma_f32_16x16x32_bf16 v[90:93], v[138:141], v[178:181], v[90:93]
	v_mfma_f32_16x16x32_bf16 v[78:81], v[130:133], v[186:189], v[78:81]
	v_mfma_f32_16x16x32_bf16 v[74:77], v[138:141], v[186:189], v[74:77]
	v_mfma_f32_16x16x32_bf16 v[126:129], v[134:137], v[166:169], v[126:129]
	v_mfma_f32_16x16x32_bf16 v[122:125], v[142:145], v[166:169], v[122:125]
	v_mfma_f32_16x16x32_bf16 v[110:113], v[134:137], v[174:177], v[110:113]
	v_mfma_f32_16x16x32_bf16 v[106:109], v[142:145], v[174:177], v[106:109]
	v_mfma_f32_16x16x32_bf16 v[94:97], v[134:137], v[182:185], v[94:97]
	v_mfma_f32_16x16x32_bf16 v[90:93], v[142:145], v[182:185], v[90:93]
	v_mfma_f32_16x16x32_bf16 v[78:81], v[134:137], v[190:193], v[78:81]
	v_mfma_f32_16x16x32_bf16 v[74:77], v[142:145], v[190:193], v[74:77]
	v_mfma_f32_16x16x32_bf16 v[118:121], v[146:149], v[162:165], v[118:121]
	v_mfma_f32_16x16x32_bf16 v[114:117], v[154:157], v[162:165], v[114:117]
	v_mfma_f32_16x16x32_bf16 v[102:105], v[146:149], v[170:173], v[102:105]
	v_mfma_f32_16x16x32_bf16 v[98:101], v[154:157], v[170:173], v[98:101]
	v_mfma_f32_16x16x32_bf16 v[86:89], v[146:149], v[178:181], v[86:89]
	v_mfma_f32_16x16x32_bf16 v[82:85], v[154:157], v[178:181], v[82:85]
	v_mfma_f32_16x16x32_bf16 v[70:73], v[146:149], v[186:189], v[70:73]
	v_mfma_f32_16x16x32_bf16 v[66:69], v[154:157], v[186:189], v[66:69]
	v_mfma_f32_16x16x32_bf16 v[118:121], v[150:153], v[166:169], v[118:121]
	v_mfma_f32_16x16x32_bf16 v[114:117], v[158:161], v[166:169], v[114:117]
	v_mfma_f32_16x16x32_bf16 v[102:105], v[150:153], v[174:177], v[102:105]
	v_mfma_f32_16x16x32_bf16 v[98:101], v[158:161], v[174:177], v[98:101]
	v_mfma_f32_16x16x32_bf16 v[86:89], v[150:153], v[182:185], v[86:89]
	v_mfma_f32_16x16x32_bf16 v[82:85], v[158:161], v[182:185], v[82:85]
	v_mfma_f32_16x16x32_bf16 v[70:73], v[150:153], v[190:193], v[70:73]
	v_mfma_f32_16x16x32_bf16 v[66:69], v[158:161], v[190:193], v[66:69]
	s_barrier
	s_add_i32 s3, s3, s12
	v_lshl_add_u64 v[194:195], v[194:195], 0, s[34:35]
	s_mov_b32 m0, s3
	ds_read_b128 v[162:165], v245 offset:49152
	ds_read_b128 v[166:169], v245 offset:50176
	ds_read_b128 v[170:173], v245 offset:51200
	ds_read_b128 v[174:177], v245 offset:52224
	ds_read_b128 v[178:181], v245 offset:53248
	ds_read_b128 v[182:185], v245 offset:54272
	ds_read_b128 v[186:189], v245 offset:55296
	ds_read_b128 v[190:193], v245 offset:56320
	global_load_lds_dwordx4 v[194:195], off
	v_lshl_add_u64 v[194:195], v[196:197], 0, s[34:35]
	s_add_i32 m0, s3, 0x2000
	s_add_i32 s3, s33, s12
	global_load_lds_dwordx4 v[194:195], off
	s_mov_b32 m0, s3
	v_lshl_add_u64 v[194:195], v[216:217], 0, s[34:35]
	global_load_lds_dwordx4 v[194:195], off
	s_add_i32 m0, s3, 0x2000
	v_lshl_add_u64 v[194:195], v[218:219], 0, s[34:35]
	global_load_lds_dwordx4 v[194:195], off
	s_mov_b32 m0, s75
	v_lshl_add_u64 v[194:195], v[220:221], 0, s[34:35]
	global_load_lds_dwordx4 v[194:195], off
	s_mov_b32 m0, s54
	v_lshl_add_u64 v[194:195], v[222:223], 0, s[34:35]
	global_load_lds_dwordx4 v[194:195], off
	s_waitcnt vmcnt(8) lgkmcnt(0)
	s_barrier
	v_mfma_f32_16x16x32_bf16 v[62:65], v[130:133], v[162:165], v[62:65]
	v_mfma_f32_16x16x32_bf16 v[58:61], v[138:141], v[162:165], v[58:61]
	v_mfma_f32_16x16x32_bf16 v[46:49], v[130:133], v[170:173], v[46:49]
	v_mfma_f32_16x16x32_bf16 v[42:45], v[138:141], v[170:173], v[42:45]
	v_mfma_f32_16x16x32_bf16 v[30:33], v[130:133], v[178:181], v[30:33]
	v_mfma_f32_16x16x32_bf16 v[26:29], v[138:141], v[178:181], v[26:29]
	v_mfma_f32_16x16x32_bf16 v[14:17], v[130:133], v[186:189], v[14:17]
	v_mfma_f32_16x16x32_bf16 v[10:13], v[138:141], v[186:189], v[10:13]
	v_mfma_f32_16x16x32_bf16 v[62:65], v[134:137], v[166:169], v[62:65]
	v_mfma_f32_16x16x32_bf16 v[58:61], v[142:145], v[166:169], v[58:61]
	v_mfma_f32_16x16x32_bf16 v[46:49], v[134:137], v[174:177], v[46:49]
	v_mfma_f32_16x16x32_bf16 v[42:45], v[142:145], v[174:177], v[42:45]
	v_mfma_f32_16x16x32_bf16 v[30:33], v[134:137], v[182:185], v[30:33]
	v_mfma_f32_16x16x32_bf16 v[26:29], v[142:145], v[182:185], v[26:29]
	v_mfma_f32_16x16x32_bf16 v[14:17], v[134:137], v[190:193], v[14:17]
	v_mfma_f32_16x16x32_bf16 v[10:13], v[142:145], v[190:193], v[10:13]
	v_mfma_f32_16x16x32_bf16 v[54:57], v[146:149], v[162:165], v[54:57]
	v_mfma_f32_16x16x32_bf16 v[50:53], v[154:157], v[162:165], v[50:53]
	v_mfma_f32_16x16x32_bf16 v[38:41], v[146:149], v[170:173], v[38:41]
	v_mfma_f32_16x16x32_bf16 v[34:37], v[154:157], v[170:173], v[34:37]
	v_mfma_f32_16x16x32_bf16 v[22:25], v[146:149], v[178:181], v[22:25]
	v_mfma_f32_16x16x32_bf16 v[18:21], v[154:157], v[178:181], v[18:21]
	v_mfma_f32_16x16x32_bf16 v[6:9], v[146:149], v[186:189], v[6:9]
	v_mfma_f32_16x16x32_bf16 v[2:5], v[154:157], v[186:189], v[2:5]
	v_mfma_f32_16x16x32_bf16 v[54:57], v[150:153], v[166:169], v[54:57]
	v_mfma_f32_16x16x32_bf16 v[50:53], v[158:161], v[166:169], v[50:53]
	v_mfma_f32_16x16x32_bf16 v[38:41], v[150:153], v[174:177], v[38:41]
	v_mfma_f32_16x16x32_bf16 v[34:37], v[158:161], v[174:177], v[34:37]
	v_mfma_f32_16x16x32_bf16 v[22:25], v[150:153], v[182:185], v[22:25]
	v_mfma_f32_16x16x32_bf16 v[18:21], v[158:161], v[182:185], v[18:21]
	v_mfma_f32_16x16x32_bf16 v[6:9], v[150:153], v[190:193], v[6:9]
	v_mfma_f32_16x16x32_bf16 v[2:5], v[158:161], v[190:193], v[2:5]
	s_barrier
	s_add_u32 s16, s16, 0x100
	s_addc_u32 s29, s29, 0
	s_add_u32 s0, s0, 0x100
	s_addc_u32 s1, s1, 0
	s_cmp_ge_u32 s2, s5
	s_mov_b32 s33, s2
	s_cbranch_scc0 .LBB0_446
	s_and_b64 vcc, exec, s[70:71]
	s_cbranch_vccz .LBB0_450
	s_barrier
	s_cmp_lt_i32 s24, 2
	s_mov_b64 s[0:1], -1
	s_cbranch_scc0 .LBB0_451
